# GEMM unit loops: 128-register accumulator clear done with v_mov_b64 pairs (64 instructions) instead of 127 single moves
# baseline (speedup 1.0000x reference)
.LBB0_288:
	s_ashr_i32 s13, s12, 31
	s_lshl_b64 s[16:17], s[12:13], 19
	s_add_u32 s16, s36, s16
	s_addc_u32 s17, s37, s17
	s_and_b64 s[18:19], s[0:1], exec
	s_cselect_b32 s13, s17, s27
	s_cselect_b32 s50, s16, s26
	s_ashr_i32 s15, s14, 31
	s_lshl_b64 s[18:19], s[14:15], 19
	s_add_u32 s18, s30, s18
	s_addc_u32 s19, s31, s19
	s_and_b64 s[28:29], s[0:1], exec
	s_cselect_b32 s15, s19, s25
	s_cselect_b32 s51, s18, s24
	s_add_u32 s52, s24, 0x10000
	s_addc_u32 s53, s25, 0
	s_add_u32 s24, s26, 0x40080
	v_mov_b32_e32 v0, 0
	s_addc_u32 s25, s27, 0
	s_mov_b32 s54, -2
	v_mov_b32_e32 v1, v0
	v_mov_b64_e32 v[2:3], v[0:1]
	v_mov_b64_e32 v[4:5], v[0:1]
	v_mov_b64_e32 v[6:7], v[0:1]
	v_mov_b64_e32 v[8:9], v[0:1]
	v_mov_b64_e32 v[10:11], v[0:1]
	v_mov_b64_e32 v[12:13], v[0:1]
	v_mov_b64_e32 v[14:15], v[0:1]
	v_mov_b64_e32 v[16:17], v[0:1]
	v_mov_b64_e32 v[18:19], v[0:1]
	v_mov_b64_e32 v[20:21], v[0:1]
	v_mov_b64_e32 v[22:23], v[0:1]
	v_mov_b64_e32 v[24:25], v[0:1]
	v_mov_b64_e32 v[26:27], v[0:1]
	v_mov_b64_e32 v[28:29], v[0:1]
	v_mov_b64_e32 v[30:31], v[0:1]
	v_mov_b64_e32 v[32:33], v[0:1]
	v_mov_b64_e32 v[34:35], v[0:1]
	v_mov_b64_e32 v[36:37], v[0:1]
	v_mov_b64_e32 v[38:39], v[0:1]
	v_mov_b64_e32 v[40:41], v[0:1]
	v_mov_b64_e32 v[42:43], v[0:1]
	v_mov_b64_e32 v[44:45], v[0:1]
	v_mov_b64_e32 v[46:47], v[0:1]
	v_mov_b64_e32 v[48:49], v[0:1]
	v_mov_b64_e32 v[50:51], v[0:1]
	v_mov_b64_e32 v[52:53], v[0:1]
	v_mov_b64_e32 v[54:55], v[0:1]
	v_mov_b64_e32 v[56:57], v[0:1]
	v_mov_b64_e32 v[58:59], v[0:1]
	v_mov_b64_e32 v[60:61], v[0:1]
	v_mov_b64_e32 v[62:63], v[0:1]
	v_mov_b64_e32 v[64:65], v[0:1]
	v_mov_b64_e32 v[66:67], v[0:1]
	v_mov_b64_e32 v[68:69], v[0:1]
	v_mov_b64_e32 v[70:71], v[0:1]
	v_mov_b64_e32 v[72:73], v[0:1]
	v_mov_b64_e32 v[74:75], v[0:1]
	v_mov_b64_e32 v[76:77], v[0:1]
	v_mov_b64_e32 v[78:79], v[0:1]
	v_mov_b64_e32 v[80:81], v[0:1]
	v_mov_b64_e32 v[82:83], v[0:1]
	v_mov_b64_e32 v[84:85], v[0:1]
	v_mov_b64_e32 v[86:87], v[0:1]
	v_mov_b64_e32 v[88:89], v[0:1]
	v_mov_b64_e32 v[90:91], v[0:1]
	v_mov_b64_e32 v[92:93], v[0:1]
	v_mov_b64_e32 v[94:95], v[0:1]
	v_mov_b64_e32 v[96:97], v[0:1]
	v_mov_b64_e32 v[98:99], v[0:1]
	v_mov_b64_e32 v[100:101], v[0:1]
	v_mov_b64_e32 v[102:103], v[0:1]
	v_mov_b64_e32 v[104:105], v[0:1]
	v_mov_b64_e32 v[106:107], v[0:1]
	v_mov_b64_e32 v[108:109], v[0:1]
	v_mov_b64_e32 v[110:111], v[0:1]
	v_mov_b64_e32 v[112:113], v[0:1]
	v_mov_b64_e32 v[114:115], v[0:1]
	v_mov_b64_e32 v[116:117], v[0:1]
	v_mov_b64_e32 v[118:119], v[0:1]
	v_mov_b64_e32 v[120:121], v[0:1]
	v_mov_b64_e32 v[122:123], v[0:1]
	v_mov_b64_e32 v[124:125], v[0:1]
	v_mov_b64_e32 v[126:127], v[0:1]

.LBB0_407:
	s_add_u32 s47, s38, 0x10000
	s_addc_u32 s48, s39, 0
	s_add_u32 s38, s40, 0xc000
	v_mov_b32_e32 v0, 0
	s_addc_u32 s39, s41, 0
	s_mov_b32 s49, -2
	v_mov_b32_e32 v1, v0
	v_mov_b64_e32 v[2:3], v[0:1]
	v_mov_b64_e32 v[4:5], v[0:1]
	v_mov_b64_e32 v[6:7], v[0:1]
	v_mov_b64_e32 v[8:9], v[0:1]
	v_mov_b64_e32 v[10:11], v[0:1]
	v_mov_b64_e32 v[12:13], v[0:1]
	v_mov_b64_e32 v[14:15], v[0:1]
	v_mov_b64_e32 v[16:17], v[0:1]
	v_mov_b64_e32 v[18:19], v[0:1]
	v_mov_b64_e32 v[20:21], v[0:1]
	v_mov_b64_e32 v[22:23], v[0:1]
	v_mov_b64_e32 v[24:25], v[0:1]
	v_mov_b64_e32 v[26:27], v[0:1]
	v_mov_b64_e32 v[28:29], v[0:1]
	v_mov_b64_e32 v[30:31], v[0:1]
	v_mov_b64_e32 v[32:33], v[0:1]
	v_mov_b64_e32 v[34:35], v[0:1]
	v_mov_b64_e32 v[36:37], v[0:1]
	v_mov_b64_e32 v[38:39], v[0:1]
	v_mov_b64_e32 v[40:41], v[0:1]
	v_mov_b64_e32 v[42:43], v[0:1]
	v_mov_b64_e32 v[44:45], v[0:1]
	v_mov_b64_e32 v[46:47], v[0:1]
	v_mov_b64_e32 v[48:49], v[0:1]
	v_mov_b64_e32 v[50:51], v[0:1]
	v_mov_b64_e32 v[52:53], v[0:1]
	v_mov_b64_e32 v[54:55], v[0:1]
	v_mov_b64_e32 v[56:57], v[0:1]
	v_mov_b64_e32 v[58:59], v[0:1]
	v_mov_b64_e32 v[60:61], v[0:1]
	v_mov_b64_e32 v[62:63], v[0:1]
	v_mov_b64_e32 v[64:65], v[0:1]
	v_mov_b64_e32 v[66:67], v[0:1]
	v_mov_b64_e32 v[68:69], v[0:1]
	v_mov_b64_e32 v[70:71], v[0:1]
	v_mov_b64_e32 v[72:73], v[0:1]
	v_mov_b64_e32 v[74:75], v[0:1]
	v_mov_b64_e32 v[76:77], v[0:1]
	v_mov_b64_e32 v[78:79], v[0:1]
	v_mov_b64_e32 v[80:81], v[0:1]
	v_mov_b64_e32 v[82:83], v[0:1]
	v_mov_b64_e32 v[84:85], v[0:1]
	v_mov_b64_e32 v[86:87], v[0:1]
	v_mov_b64_e32 v[88:89], v[0:1]
	v_mov_b64_e32 v[90:91], v[0:1]
	v_mov_b64_e32 v[92:93], v[0:1]
	v_mov_b64_e32 v[94:95], v[0:1]
	v_mov_b64_e32 v[96:97], v[0:1]
	v_mov_b64_e32 v[98:99], v[0:1]
	v_mov_b64_e32 v[100:101], v[0:1]
	v_mov_b64_e32 v[102:103], v[0:1]
	v_mov_b64_e32 v[104:105], v[0:1]
	v_mov_b64_e32 v[106:107], v[0:1]
	v_mov_b64_e32 v[108:109], v[0:1]
	v_mov_b64_e32 v[110:111], v[0:1]
	v_mov_b64_e32 v[112:113], v[0:1]
	v_mov_b64_e32 v[114:115], v[0:1]
	v_mov_b64_e32 v[116:117], v[0:1]
	v_mov_b64_e32 v[118:119], v[0:1]
	v_mov_b64_e32 v[120:121], v[0:1]
	v_mov_b64_e32 v[122:123], v[0:1]
	v_mov_b64_e32 v[124:125], v[0:1]
	v_mov_b64_e32 v[126:127], v[0:1]

.LBB0_491:
	s_ashr_i32 s23, s22, 31
	s_lshl_b64 s[26:27], s[22:23], 19
	s_add_u32 s26, s42, s26
	s_addc_u32 s27, s43, s27
	s_and_b64 s[28:29], s[4:5], exec
	s_cselect_b32 s1, s27, s35
	s_cselect_b32 s7, s26, s34
	s_ashr_i32 s25, s24, 31
	s_lshl_b64 s[28:29], s[24:25], 19
	s_add_u32 s28, s44, s28
	s_addc_u32 s29, s45, s29
	s_and_b64 s[36:37], s[4:5], exec
	s_cselect_b32 s10, s29, s31
	s_cselect_b32 s23, s28, s30
	s_add_u32 s25, s30, 0x10000
	s_addc_u32 s38, s31, 0
	s_add_u32 s30, s34, 0x40080
	v_mov_b32_e32 v0, 0
	s_addc_u32 s31, s35, 0
	s_mov_b32 s39, -2
	v_mov_b32_e32 v1, v0
	v_mov_b64_e32 v[2:3], v[0:1]
	v_mov_b64_e32 v[4:5], v[0:1]
	v_mov_b64_e32 v[6:7], v[0:1]
	v_mov_b64_e32 v[8:9], v[0:1]
	v_mov_b64_e32 v[10:11], v[0:1]
	v_mov_b64_e32 v[12:13], v[0:1]
	v_mov_b64_e32 v[14:15], v[0:1]
	v_mov_b64_e32 v[16:17], v[0:1]
	v_mov_b64_e32 v[18:19], v[0:1]
	v_mov_b64_e32 v[20:21], v[0:1]
	v_mov_b64_e32 v[22:23], v[0:1]
	v_mov_b64_e32 v[24:25], v[0:1]
	v_mov_b64_e32 v[26:27], v[0:1]
	v_mov_b64_e32 v[28:29], v[0:1]
	v_mov_b64_e32 v[30:31], v[0:1]
	v_mov_b64_e32 v[32:33], v[0:1]
	v_mov_b64_e32 v[34:35], v[0:1]
	v_mov_b64_e32 v[36:37], v[0:1]
	v_mov_b64_e32 v[38:39], v[0:1]
	v_mov_b64_e32 v[40:41], v[0:1]
	v_mov_b64_e32 v[42:43], v[0:1]
	v_mov_b64_e32 v[44:45], v[0:1]
	v_mov_b64_e32 v[46:47], v[0:1]
	v_mov_b64_e32 v[48:49], v[0:1]
	v_mov_b64_e32 v[50:51], v[0:1]
	v_mov_b64_e32 v[52:53], v[0:1]
	v_mov_b64_e32 v[54:55], v[0:1]
	v_mov_b64_e32 v[56:57], v[0:1]
	v_mov_b64_e32 v[58:59], v[0:1]
	v_mov_b64_e32 v[60:61], v[0:1]
	v_mov_b64_e32 v[62:63], v[0:1]
	v_mov_b64_e32 v[64:65], v[0:1]
	v_mov_b64_e32 v[66:67], v[0:1]
	v_mov_b64_e32 v[68:69], v[0:1]
	v_mov_b64_e32 v[70:71], v[0:1]
	v_mov_b64_e32 v[72:73], v[0:1]
	v_mov_b64_e32 v[74:75], v[0:1]
	v_mov_b64_e32 v[76:77], v[0:1]
	v_mov_b64_e32 v[78:79], v[0:1]
	v_mov_b64_e32 v[80:81], v[0:1]
	v_mov_b64_e32 v[82:83], v[0:1]
	v_mov_b64_e32 v[84:85], v[0:1]
	v_mov_b64_e32 v[86:87], v[0:1]
	v_mov_b64_e32 v[88:89], v[0:1]
	v_mov_b64_e32 v[90:91], v[0:1]
	v_mov_b64_e32 v[92:93], v[0:1]
	v_mov_b64_e32 v[94:95], v[0:1]
	v_mov_b64_e32 v[96:97], v[0:1]
	v_mov_b64_e32 v[98:99], v[0:1]
	v_mov_b64_e32 v[100:101], v[0:1]
	v_mov_b64_e32 v[102:103], v[0:1]
	v_mov_b64_e32 v[104:105], v[0:1]
	v_mov_b64_e32 v[106:107], v[0:1]
	v_mov_b64_e32 v[108:109], v[0:1]
	v_mov_b64_e32 v[110:111], v[0:1]
	v_mov_b64_e32 v[112:113], v[0:1]
	v_mov_b64_e32 v[114:115], v[0:1]
	v_mov_b64_e32 v[116:117], v[0:1]
	v_mov_b64_e32 v[118:119], v[0:1]
	v_mov_b64_e32 v[120:121], v[0:1]
	v_mov_b64_e32 v[122:123], v[0:1]
	v_mov_b64_e32 v[124:125], v[0:1]
	v_mov_b64_e32 v[126:127], v[0:1]

.LBB0_1070:
	s_ashr_i32 s17, s16, 31
	s_lshl_b64 s[20:21], s[16:17], 18
	s_add_u32 s20, s38, s20
	s_addc_u32 s21, s39, s21
	s_and_b64 s[22:23], s[0:1], exec
	s_cselect_b32 s17, s21, s31
	s_cselect_b32 s52, s20, s30
	s_ashr_i32 s19, s18, 31
	s_lshl_b64 s[22:23], s[18:19], 18
	s_add_u32 s22, s40, s22
	s_addc_u32 s23, s41, s23
	s_and_b64 s[34:35], s[0:1], exec
	s_cselect_b32 s19, s23, s29
	s_cselect_b32 s53, s22, s28
	s_add_u32 s54, s28, 0x10000
	s_addc_u32 s55, s29, 0
	s_add_u32 s28, s30, 0x20080
	v_mov_b32_e32 v0, 0
	s_addc_u32 s29, s31, 0
	s_mov_b32 s56, -2
	v_mov_b32_e32 v1, v0
	v_mov_b64_e32 v[2:3], v[0:1]
	v_mov_b64_e32 v[4:5], v[0:1]
	v_mov_b64_e32 v[6:7], v[0:1]
	v_mov_b64_e32 v[8:9], v[0:1]
	v_mov_b64_e32 v[10:11], v[0:1]
	v_mov_b64_e32 v[12:13], v[0:1]
	v_mov_b64_e32 v[14:15], v[0:1]
	v_mov_b64_e32 v[16:17], v[0:1]
	v_mov_b64_e32 v[18:19], v[0:1]
	v_mov_b64_e32 v[20:21], v[0:1]
	v_mov_b64_e32 v[22:23], v[0:1]
	v_mov_b64_e32 v[24:25], v[0:1]
	v_mov_b64_e32 v[26:27], v[0:1]
	v_mov_b64_e32 v[28:29], v[0:1]
	v_mov_b64_e32 v[30:31], v[0:1]
	v_mov_b64_e32 v[32:33], v[0:1]
	v_mov_b64_e32 v[34:35], v[0:1]
	v_mov_b64_e32 v[36:37], v[0:1]
	v_mov_b64_e32 v[38:39], v[0:1]
	v_mov_b64_e32 v[40:41], v[0:1]
	v_mov_b64_e32 v[42:43], v[0:1]
	v_mov_b64_e32 v[44:45], v[0:1]
	v_mov_b64_e32 v[46:47], v[0:1]
	v_mov_b64_e32 v[48:49], v[0:1]
	v_mov_b64_e32 v[50:51], v[0:1]
	v_mov_b64_e32 v[52:53], v[0:1]
	v_mov_b64_e32 v[54:55], v[0:1]
	v_mov_b64_e32 v[56:57], v[0:1]
	v_mov_b64_e32 v[58:59], v[0:1]
	v_mov_b64_e32 v[60:61], v[0:1]
	v_mov_b64_e32 v[62:63], v[0:1]
	v_mov_b64_e32 v[64:65], v[0:1]
	v_mov_b64_e32 v[66:67], v[0:1]
	v_mov_b64_e32 v[68:69], v[0:1]
	v_mov_b64_e32 v[70:71], v[0:1]
	v_mov_b64_e32 v[72:73], v[0:1]
	v_mov_b64_e32 v[74:75], v[0:1]
	v_mov_b64_e32 v[76:77], v[0:1]
	v_mov_b64_e32 v[78:79], v[0:1]
	v_mov_b64_e32 v[80:81], v[0:1]
	v_mov_b64_e32 v[82:83], v[0:1]
	v_mov_b64_e32 v[84:85], v[0:1]
	v_mov_b64_e32 v[86:87], v[0:1]
	v_mov_b64_e32 v[88:89], v[0:1]
	v_mov_b64_e32 v[90:91], v[0:1]
	v_mov_b64_e32 v[92:93], v[0:1]
	v_mov_b64_e32 v[94:95], v[0:1]
	v_mov_b64_e32 v[96:97], v[0:1]
	v_mov_b64_e32 v[98:99], v[0:1]
	v_mov_b64_e32 v[100:101], v[0:1]
	v_mov_b64_e32 v[102:103], v[0:1]
	v_mov_b64_e32 v[104:105], v[0:1]
	v_mov_b64_e32 v[106:107], v[0:1]
	v_mov_b64_e32 v[108:109], v[0:1]
	v_mov_b64_e32 v[110:111], v[0:1]
	v_mov_b64_e32 v[112:113], v[0:1]
	v_mov_b64_e32 v[114:115], v[0:1]
	v_mov_b64_e32 v[116:117], v[0:1]
	v_mov_b64_e32 v[118:119], v[0:1]
	v_mov_b64_e32 v[120:121], v[0:1]
	v_mov_b64_e32 v[122:123], v[0:1]
	v_mov_b64_e32 v[124:125], v[0:1]
	v_mov_b64_e32 v[126:127], v[0:1]

.LBB0_1094:
	s_ashr_i32 s15, s14, 31
	s_lshl_b64 s[18:19], s[14:15], 18
	s_add_u32 s18, s35, s18
	s_addc_u32 s19, s37, s19
	s_and_b64 s[20:21], s[0:1], exec
	s_cselect_b32 s15, s19, s29
	s_cselect_b32 s50, s18, s28
	s_ashr_i32 s17, s16, 31
	s_lshl_b64 s[20:21], s[16:17], 18
	s_add_u32 s20, s38, s20
	s_addc_u32 s21, s39, s21
	s_and_b64 s[30:31], s[0:1], exec
	s_cselect_b32 s17, s21, s27
	s_cselect_b32 s51, s20, s26
	s_add_u32 s52, s26, 0x10000
	s_addc_u32 s53, s27, 0
	s_add_u32 s26, s28, 0x20080
	v_mov_b32_e32 v0, 0
	s_addc_u32 s27, s29, 0
	s_mov_b32 s54, -2
	v_mov_b32_e32 v1, v0
	v_mov_b64_e32 v[2:3], v[0:1]
	v_mov_b64_e32 v[4:5], v[0:1]
	v_mov_b64_e32 v[6:7], v[0:1]
	v_mov_b64_e32 v[8:9], v[0:1]
	v_mov_b64_e32 v[10:11], v[0:1]
	v_mov_b64_e32 v[12:13], v[0:1]
	v_mov_b64_e32 v[14:15], v[0:1]
	v_mov_b64_e32 v[16:17], v[0:1]
	v_mov_b64_e32 v[18:19], v[0:1]
	v_mov_b64_e32 v[20:21], v[0:1]
	v_mov_b64_e32 v[22:23], v[0:1]
	v_mov_b64_e32 v[24:25], v[0:1]
	v_mov_b64_e32 v[26:27], v[0:1]
	v_mov_b64_e32 v[28:29], v[0:1]
	v_mov_b64_e32 v[30:31], v[0:1]
	v_mov_b64_e32 v[32:33], v[0:1]
	v_mov_b64_e32 v[34:35], v[0:1]
	v_mov_b64_e32 v[36:37], v[0:1]
	v_mov_b64_e32 v[38:39], v[0:1]
	v_mov_b64_e32 v[40:41], v[0:1]
	v_mov_b64_e32 v[42:43], v[0:1]
	v_mov_b64_e32 v[44:45], v[0:1]
	v_mov_b64_e32 v[46:47], v[0:1]
	v_mov_b64_e32 v[48:49], v[0:1]
	v_mov_b64_e32 v[50:51], v[0:1]
	v_mov_b64_e32 v[52:53], v[0:1]
	v_mov_b64_e32 v[54:55], v[0:1]
	v_mov_b64_e32 v[56:57], v[0:1]
	v_mov_b64_e32 v[58:59], v[0:1]
	v_mov_b64_e32 v[60:61], v[0:1]
	v_mov_b64_e32 v[62:63], v[0:1]
	v_mov_b64_e32 v[64:65], v[0:1]
	v_mov_b64_e32 v[66:67], v[0:1]
	v_mov_b64_e32 v[68:69], v[0:1]
	v_mov_b64_e32 v[70:71], v[0:1]
	v_mov_b64_e32 v[72:73], v[0:1]
	v_mov_b64_e32 v[74:75], v[0:1]
	v_mov_b64_e32 v[76:77], v[0:1]
	v_mov_b64_e32 v[78:79], v[0:1]
	v_mov_b64_e32 v[80:81], v[0:1]
	v_mov_b64_e32 v[82:83], v[0:1]
	v_mov_b64_e32 v[84:85], v[0:1]
	v_mov_b64_e32 v[86:87], v[0:1]
	v_mov_b64_e32 v[88:89], v[0:1]
	v_mov_b64_e32 v[90:91], v[0:1]
	v_mov_b64_e32 v[92:93], v[0:1]
	v_mov_b64_e32 v[94:95], v[0:1]
	v_mov_b64_e32 v[96:97], v[0:1]
	v_mov_b64_e32 v[98:99], v[0:1]
	v_mov_b64_e32 v[100:101], v[0:1]
	v_mov_b64_e32 v[102:103], v[0:1]
	v_mov_b64_e32 v[104:105], v[0:1]
	v_mov_b64_e32 v[106:107], v[0:1]
	v_mov_b64_e32 v[108:109], v[0:1]
	v_mov_b64_e32 v[110:111], v[0:1]
	v_mov_b64_e32 v[112:113], v[0:1]
	v_mov_b64_e32 v[114:115], v[0:1]
	v_mov_b64_e32 v[116:117], v[0:1]
	v_mov_b64_e32 v[118:119], v[0:1]
	v_mov_b64_e32 v[120:121], v[0:1]
	v_mov_b64_e32 v[122:123], v[0:1]
	v_mov_b64_e32 v[124:125], v[0:1]
	v_mov_b64_e32 v[126:127], v[0:1]

.LBB0_1170:
	s_ashr_i32 s35, s34, 31
	s_lshl_b64 s[38:39], s[34:35], 19
	s_add_u32 s38, s60, s38
	s_addc_u32 s39, s61, s39
	s_and_b64 s[40:41], s[8:9], exec
	s_cselect_b32 s35, s39, s49
	s_cselect_b32 s43, s38, s48
	s_ashr_i32 s37, s36, 31
	s_lshl_b64 s[40:41], s[36:37], 19
	s_add_u32 s40, s62, s40
	s_addc_u32 s41, s63, s41
	s_and_b64 s[50:51], s[8:9], exec
	s_cselect_b32 s37, s41, s47
	s_cselect_b32 s45, s40, s46
	s_add_u32 s52, s46, 0x10000
	s_addc_u32 s53, s47, 0
	s_add_u32 s46, s48, 0x40080
	v_mov_b32_e32 v0, 0
	s_addc_u32 s47, s49, 0
	s_mov_b32 s54, -2
	v_mov_b32_e32 v1, v0
	v_mov_b64_e32 v[2:3], v[0:1]
	v_mov_b64_e32 v[4:5], v[0:1]
	v_mov_b64_e32 v[6:7], v[0:1]
	v_mov_b64_e32 v[8:9], v[0:1]
	v_mov_b64_e32 v[10:11], v[0:1]
	v_mov_b64_e32 v[12:13], v[0:1]
	v_mov_b64_e32 v[14:15], v[0:1]
	v_mov_b64_e32 v[16:17], v[0:1]
	v_mov_b64_e32 v[18:19], v[0:1]
	v_mov_b64_e32 v[20:21], v[0:1]
	v_mov_b64_e32 v[22:23], v[0:1]
	v_mov_b64_e32 v[24:25], v[0:1]
	v_mov_b64_e32 v[26:27], v[0:1]
	v_mov_b64_e32 v[28:29], v[0:1]
	v_mov_b64_e32 v[30:31], v[0:1]
	v_mov_b64_e32 v[32:33], v[0:1]
	v_mov_b64_e32 v[34:35], v[0:1]
	v_mov_b64_e32 v[36:37], v[0:1]
	v_mov_b64_e32 v[38:39], v[0:1]
	v_mov_b64_e32 v[40:41], v[0:1]
	v_mov_b64_e32 v[42:43], v[0:1]
	v_mov_b64_e32 v[44:45], v[0:1]
	v_mov_b64_e32 v[46:47], v[0:1]
	v_mov_b64_e32 v[48:49], v[0:1]
	v_mov_b64_e32 v[50:51], v[0:1]
	v_mov_b64_e32 v[52:53], v[0:1]
	v_mov_b64_e32 v[54:55], v[0:1]
	v_mov_b64_e32 v[56:57], v[0:1]
	v_mov_b64_e32 v[58:59], v[0:1]
	v_mov_b64_e32 v[60:61], v[0:1]
	v_mov_b64_e32 v[62:63], v[0:1]
	v_mov_b64_e32 v[64:65], v[0:1]
	v_mov_b64_e32 v[66:67], v[0:1]
	v_mov_b64_e32 v[68:69], v[0:1]
	v_mov_b64_e32 v[70:71], v[0:1]
	v_mov_b64_e32 v[72:73], v[0:1]
	v_mov_b64_e32 v[74:75], v[0:1]
	v_mov_b64_e32 v[76:77], v[0:1]
	v_mov_b64_e32 v[78:79], v[0:1]
	v_mov_b64_e32 v[80:81], v[0:1]
	v_mov_b64_e32 v[82:83], v[0:1]
	v_mov_b64_e32 v[84:85], v[0:1]
	v_mov_b64_e32 v[86:87], v[0:1]
	v_mov_b64_e32 v[88:89], v[0:1]
	v_mov_b64_e32 v[90:91], v[0:1]
	v_mov_b64_e32 v[92:93], v[0:1]
	v_mov_b64_e32 v[94:95], v[0:1]
	v_mov_b64_e32 v[96:97], v[0:1]
	v_mov_b64_e32 v[98:99], v[0:1]
	v_mov_b64_e32 v[100:101], v[0:1]
	v_mov_b64_e32 v[102:103], v[0:1]
	v_mov_b64_e32 v[104:105], v[0:1]
	v_mov_b64_e32 v[106:107], v[0:1]
	v_mov_b64_e32 v[108:109], v[0:1]
	v_mov_b64_e32 v[110:111], v[0:1]
	v_mov_b64_e32 v[112:113], v[0:1]
	v_mov_b64_e32 v[114:115], v[0:1]
	v_mov_b64_e32 v[116:117], v[0:1]
	v_mov_b64_e32 v[118:119], v[0:1]
	v_mov_b64_e32 v[120:121], v[0:1]
	v_mov_b64_e32 v[122:123], v[0:1]
	v_mov_b64_e32 v[124:125], v[0:1]
	v_mov_b64_e32 v[126:127], v[0:1]

.LBB0_1252:
	s_ashr_i32 s11, s10, 31
	s_lshl_b64 s[16:17], s[10:11], 19
	s_add_u32 s16, s30, s16
	s_addc_u32 s17, s31, s17
	s_and_b64 s[18:19], s[0:1], exec
	s_cselect_b32 s11, s17, s27
	s_cselect_b32 s50, s16, s26
	s_ashr_i32 s13, s12, 31
	s_lshl_b64 s[18:19], s[12:13], 19
	s_add_u32 s18, s33, s18
	s_addc_u32 s19, s34, s19
	s_and_b64 s[28:29], s[0:1], exec
	s_cselect_b32 s13, s19, s25
	s_cselect_b32 s51, s18, s24
	s_add_u32 s52, s24, 0x10000
	s_addc_u32 s53, s25, 0
	s_add_u32 s24, s26, 0x40080
	v_mov_b32_e32 v0, 0
	s_addc_u32 s25, s27, 0
	s_mov_b32 s54, -2
	v_mov_b32_e32 v1, v0
	v_mov_b64_e32 v[2:3], v[0:1]
	v_mov_b64_e32 v[4:5], v[0:1]
	v_mov_b64_e32 v[6:7], v[0:1]
	v_mov_b64_e32 v[8:9], v[0:1]
	v_mov_b64_e32 v[10:11], v[0:1]
	v_mov_b64_e32 v[12:13], v[0:1]
	v_mov_b64_e32 v[14:15], v[0:1]
	v_mov_b64_e32 v[16:17], v[0:1]
	v_mov_b64_e32 v[18:19], v[0:1]
	v_mov_b64_e32 v[20:21], v[0:1]
	v_mov_b64_e32 v[22:23], v[0:1]
	v_mov_b64_e32 v[24:25], v[0:1]
	v_mov_b64_e32 v[26:27], v[0:1]
	v_mov_b64_e32 v[28:29], v[0:1]
	v_mov_b64_e32 v[30:31], v[0:1]
	v_mov_b64_e32 v[32:33], v[0:1]
	v_mov_b64_e32 v[34:35], v[0:1]
	v_mov_b64_e32 v[36:37], v[0:1]
	v_mov_b64_e32 v[38:39], v[0:1]
	v_mov_b64_e32 v[40:41], v[0:1]
	v_mov_b64_e32 v[42:43], v[0:1]
	v_mov_b64_e32 v[44:45], v[0:1]
	v_mov_b64_e32 v[46:47], v[0:1]
	v_mov_b64_e32 v[48:49], v[0:1]
	v_mov_b64_e32 v[50:51], v[0:1]
	v_mov_b64_e32 v[52:53], v[0:1]
	v_mov_b64_e32 v[54:55], v[0:1]
	v_mov_b64_e32 v[56:57], v[0:1]
	v_mov_b64_e32 v[58:59], v[0:1]
	v_mov_b64_e32 v[60:61], v[0:1]
	v_mov_b64_e32 v[62:63], v[0:1]
	v_mov_b64_e32 v[64:65], v[0:1]
	v_mov_b64_e32 v[66:67], v[0:1]
	v_mov_b64_e32 v[68:69], v[0:1]
	v_mov_b64_e32 v[70:71], v[0:1]
	v_mov_b64_e32 v[72:73], v[0:1]
	v_mov_b64_e32 v[74:75], v[0:1]
	v_mov_b64_e32 v[76:77], v[0:1]
	v_mov_b64_e32 v[78:79], v[0:1]
	v_mov_b64_e32 v[80:81], v[0:1]
	v_mov_b64_e32 v[82:83], v[0:1]
	v_mov_b64_e32 v[84:85], v[0:1]
	v_mov_b64_e32 v[86:87], v[0:1]
	v_mov_b64_e32 v[88:89], v[0:1]
	v_mov_b64_e32 v[90:91], v[0:1]
	v_mov_b64_e32 v[92:93], v[0:1]
	v_mov_b64_e32 v[94:95], v[0:1]
	v_mov_b64_e32 v[96:97], v[0:1]
	v_mov_b64_e32 v[98:99], v[0:1]
	v_mov_b64_e32 v[100:101], v[0:1]
	v_mov_b64_e32 v[102:103], v[0:1]
	v_mov_b64_e32 v[104:105], v[0:1]
	v_mov_b64_e32 v[106:107], v[0:1]
	v_mov_b64_e32 v[108:109], v[0:1]
	v_mov_b64_e32 v[110:111], v[0:1]
	v_mov_b64_e32 v[112:113], v[0:1]
	v_mov_b64_e32 v[114:115], v[0:1]
	v_mov_b64_e32 v[116:117], v[0:1]
	v_mov_b64_e32 v[118:119], v[0:1]
	v_mov_b64_e32 v[120:121], v[0:1]
	v_mov_b64_e32 v[122:123], v[0:1]
	v_mov_b64_e32 v[124:125], v[0:1]
	v_mov_b64_e32 v[126:127], v[0:1]

.LBB0_1480:
	s_add_u32 s68, s36, 0x10000
	s_addc_u32 s69, s37, 0
	s_add_u32 s36, s38, 0xc000
	v_mov_b32_e32 v0, 0
	s_addc_u32 s37, s39, 0
	s_mov_b32 s70, -2
	v_mov_b32_e32 v1, v0
	v_mov_b64_e32 v[2:3], v[0:1]
	v_mov_b64_e32 v[4:5], v[0:1]
	v_mov_b64_e32 v[6:7], v[0:1]
	v_mov_b64_e32 v[8:9], v[0:1]
	v_mov_b64_e32 v[10:11], v[0:1]
	v_mov_b64_e32 v[12:13], v[0:1]
	v_mov_b64_e32 v[14:15], v[0:1]
	v_mov_b64_e32 v[16:17], v[0:1]
	v_mov_b64_e32 v[18:19], v[0:1]
	v_mov_b64_e32 v[20:21], v[0:1]
	v_mov_b64_e32 v[22:23], v[0:1]
	v_mov_b64_e32 v[24:25], v[0:1]
	v_mov_b64_e32 v[26:27], v[0:1]
	v_mov_b64_e32 v[28:29], v[0:1]
	v_mov_b64_e32 v[30:31], v[0:1]
	v_mov_b64_e32 v[32:33], v[0:1]
	v_mov_b64_e32 v[34:35], v[0:1]
	v_mov_b64_e32 v[36:37], v[0:1]
	v_mov_b64_e32 v[38:39], v[0:1]
	v_mov_b64_e32 v[40:41], v[0:1]
	v_mov_b64_e32 v[42:43], v[0:1]
	v_mov_b64_e32 v[44:45], v[0:1]
	v_mov_b64_e32 v[46:47], v[0:1]
	v_mov_b64_e32 v[48:49], v[0:1]
	v_mov_b64_e32 v[50:51], v[0:1]
	v_mov_b64_e32 v[52:53], v[0:1]
	v_mov_b64_e32 v[54:55], v[0:1]
	v_mov_b64_e32 v[56:57], v[0:1]
	v_mov_b64_e32 v[58:59], v[0:1]
	v_mov_b64_e32 v[60:61], v[0:1]
	v_mov_b64_e32 v[62:63], v[0:1]
	v_mov_b64_e32 v[64:65], v[0:1]
	v_mov_b64_e32 v[66:67], v[0:1]
	v_mov_b64_e32 v[68:69], v[0:1]
	v_mov_b64_e32 v[70:71], v[0:1]
	v_mov_b64_e32 v[72:73], v[0:1]
	v_mov_b64_e32 v[74:75], v[0:1]
	v_mov_b64_e32 v[76:77], v[0:1]
	v_mov_b64_e32 v[78:79], v[0:1]
	v_mov_b64_e32 v[80:81], v[0:1]
	v_mov_b64_e32 v[82:83], v[0:1]
	v_mov_b64_e32 v[84:85], v[0:1]
	v_mov_b64_e32 v[86:87], v[0:1]
	v_mov_b64_e32 v[88:89], v[0:1]
	v_mov_b64_e32 v[90:91], v[0:1]
	v_mov_b64_e32 v[92:93], v[0:1]
	v_mov_b64_e32 v[94:95], v[0:1]
	v_mov_b64_e32 v[96:97], v[0:1]
	v_mov_b64_e32 v[98:99], v[0:1]
	v_mov_b64_e32 v[100:101], v[0:1]
	v_mov_b64_e32 v[102:103], v[0:1]
	v_mov_b64_e32 v[104:105], v[0:1]
	v_mov_b64_e32 v[106:107], v[0:1]
	v_mov_b64_e32 v[108:109], v[0:1]
	v_mov_b64_e32 v[110:111], v[0:1]
	v_mov_b64_e32 v[112:113], v[0:1]
	v_mov_b64_e32 v[114:115], v[0:1]
	v_mov_b64_e32 v[116:117], v[0:1]
	v_mov_b64_e32 v[118:119], v[0:1]
	v_mov_b64_e32 v[120:121], v[0:1]
	v_mov_b64_e32 v[122:123], v[0:1]
	v_mov_b64_e32 v[124:125], v[0:1]
	v_mov_b64_e32 v[126:127], v[0:1]

.LBB0_1562:
	s_ashr_i32 s9, s8, 31
	s_lshl_b64 s[12:13], s[8:9], 19
	s_add_u32 s12, s28, s12
	s_addc_u32 s13, s29, s13
	s_cmp_eq_u32 s53, 2
	s_cselect_b32 s55, 0x40000, 0
	s_add_u32 s12, s12, s55
	s_addc_u32 s13, s13, 0
	s_and_b64 s[14:15], s[0:1], exec
	s_cselect_b32 s9, s13, s23
	s_cselect_b32 s45, s12, s22
	s_ashr_i32 s11, s10, 31
	s_lshl_b64 s[14:15], s[10:11], 19
	s_add_u32 s14, s30, s14
	s_addc_u32 s15, s31, s15
	s_and_b64 s[24:25], s[0:1], exec
	s_cselect_b32 s11, s15, s21
	s_cselect_b32 s46, s14, s20
	s_add_u32 s47, s20, 0x10000
	s_addc_u32 s48, s21, 0
	s_add_u32 s20, s22, 0x40080
	v_mov_b32_e32 v0, 0
	s_addc_u32 s21, s23, 0
	s_mov_b32 s49, -2
	v_mov_b32_e32 v1, v0
	v_mov_b64_e32 v[2:3], v[0:1]
	v_mov_b64_e32 v[4:5], v[0:1]
	v_mov_b64_e32 v[6:7], v[0:1]
	v_mov_b64_e32 v[8:9], v[0:1]
	v_mov_b64_e32 v[10:11], v[0:1]
	v_mov_b64_e32 v[12:13], v[0:1]
	v_mov_b64_e32 v[14:15], v[0:1]
	v_mov_b64_e32 v[16:17], v[0:1]
	v_mov_b64_e32 v[18:19], v[0:1]
	v_mov_b64_e32 v[20:21], v[0:1]
	v_mov_b64_e32 v[22:23], v[0:1]
	v_mov_b64_e32 v[24:25], v[0:1]
	v_mov_b64_e32 v[26:27], v[0:1]
	v_mov_b64_e32 v[28:29], v[0:1]
	v_mov_b64_e32 v[30:31], v[0:1]
	v_mov_b64_e32 v[32:33], v[0:1]
	v_mov_b64_e32 v[34:35], v[0:1]
	v_mov_b64_e32 v[36:37], v[0:1]
	v_mov_b64_e32 v[38:39], v[0:1]
	v_mov_b64_e32 v[40:41], v[0:1]
	v_mov_b64_e32 v[42:43], v[0:1]
	v_mov_b64_e32 v[44:45], v[0:1]
	v_mov_b64_e32 v[46:47], v[0:1]
	v_mov_b64_e32 v[48:49], v[0:1]
	v_mov_b64_e32 v[50:51], v[0:1]
	v_mov_b64_e32 v[52:53], v[0:1]
	v_mov_b64_e32 v[54:55], v[0:1]
	v_mov_b64_e32 v[56:57], v[0:1]
	v_mov_b64_e32 v[58:59], v[0:1]
	v_mov_b64_e32 v[60:61], v[0:1]
	v_mov_b64_e32 v[62:63], v[0:1]
	v_mov_b64_e32 v[64:65], v[0:1]
	v_mov_b64_e32 v[66:67], v[0:1]
	v_mov_b64_e32 v[68:69], v[0:1]
	v_mov_b64_e32 v[70:71], v[0:1]
	v_mov_b64_e32 v[72:73], v[0:1]
	v_mov_b64_e32 v[74:75], v[0:1]
	v_mov_b64_e32 v[76:77], v[0:1]
	v_mov_b64_e32 v[78:79], v[0:1]
	v_mov_b64_e32 v[80:81], v[0:1]
	v_mov_b64_e32 v[82:83], v[0:1]
	v_mov_b64_e32 v[84:85], v[0:1]
	v_mov_b64_e32 v[86:87], v[0:1]
	v_mov_b64_e32 v[88:89], v[0:1]
	v_mov_b64_e32 v[90:91], v[0:1]
	v_mov_b64_e32 v[92:93], v[0:1]
	v_mov_b64_e32 v[94:95], v[0:1]
	v_mov_b64_e32 v[96:97], v[0:1]
	v_mov_b64_e32 v[98:99], v[0:1]
	v_mov_b64_e32 v[100:101], v[0:1]
	v_mov_b64_e32 v[102:103], v[0:1]
	v_mov_b64_e32 v[104:105], v[0:1]
	v_mov_b64_e32 v[106:107], v[0:1]
	v_mov_b64_e32 v[108:109], v[0:1]
	v_mov_b64_e32 v[110:111], v[0:1]
	v_mov_b64_e32 v[112:113], v[0:1]
	v_mov_b64_e32 v[114:115], v[0:1]
	v_mov_b64_e32 v[116:117], v[0:1]
	v_mov_b64_e32 v[118:119], v[0:1]
	v_mov_b64_e32 v[120:121], v[0:1]
	v_mov_b64_e32 v[122:123], v[0:1]
	v_mov_b64_e32 v[124:125], v[0:1]
	v_mov_b64_e32 v[126:127], v[0:1]

.LBB0_1644:
	s_add_u32 s45, s36, 0x10000
	s_addc_u32 s46, s37, 0
	s_add_u32 s36, s38, 0xc000
	v_mov_b32_e32 v0, 0
	s_addc_u32 s37, s39, 0
	s_mov_b32 s47, -2
	v_mov_b32_e32 v1, v0
	v_mov_b64_e32 v[2:3], v[0:1]
	v_mov_b64_e32 v[4:5], v[0:1]
	v_mov_b64_e32 v[6:7], v[0:1]
	v_mov_b64_e32 v[8:9], v[0:1]
	v_mov_b64_e32 v[10:11], v[0:1]
	v_mov_b64_e32 v[12:13], v[0:1]
	v_mov_b64_e32 v[14:15], v[0:1]
	v_mov_b64_e32 v[16:17], v[0:1]
	v_mov_b64_e32 v[18:19], v[0:1]
	v_mov_b64_e32 v[20:21], v[0:1]
	v_mov_b64_e32 v[22:23], v[0:1]
	v_mov_b64_e32 v[24:25], v[0:1]
	v_mov_b64_e32 v[26:27], v[0:1]
	v_mov_b64_e32 v[28:29], v[0:1]
	v_mov_b64_e32 v[30:31], v[0:1]
	v_mov_b64_e32 v[32:33], v[0:1]
	v_mov_b64_e32 v[34:35], v[0:1]
	v_mov_b64_e32 v[36:37], v[0:1]
	v_mov_b64_e32 v[38:39], v[0:1]
	v_mov_b64_e32 v[40:41], v[0:1]
	v_mov_b64_e32 v[42:43], v[0:1]
	v_mov_b64_e32 v[44:45], v[0:1]
	v_mov_b64_e32 v[46:47], v[0:1]
	v_mov_b64_e32 v[48:49], v[0:1]
	v_mov_b64_e32 v[50:51], v[0:1]
	v_mov_b64_e32 v[52:53], v[0:1]
	v_mov_b64_e32 v[54:55], v[0:1]
	v_mov_b64_e32 v[56:57], v[0:1]
	v_mov_b64_e32 v[58:59], v[0:1]
	v_mov_b64_e32 v[60:61], v[0:1]
	v_mov_b64_e32 v[62:63], v[0:1]
	v_mov_b64_e32 v[64:65], v[0:1]
	v_mov_b64_e32 v[66:67], v[0:1]
	v_mov_b64_e32 v[68:69], v[0:1]
	v_mov_b64_e32 v[70:71], v[0:1]
	v_mov_b64_e32 v[72:73], v[0:1]
	v_mov_b64_e32 v[74:75], v[0:1]
	v_mov_b64_e32 v[76:77], v[0:1]
	v_mov_b64_e32 v[78:79], v[0:1]
	v_mov_b64_e32 v[80:81], v[0:1]
	v_mov_b64_e32 v[82:83], v[0:1]
	v_mov_b64_e32 v[84:85], v[0:1]
	v_mov_b64_e32 v[86:87], v[0:1]
	v_mov_b64_e32 v[88:89], v[0:1]
	v_mov_b64_e32 v[90:91], v[0:1]
	v_mov_b64_e32 v[92:93], v[0:1]
	v_mov_b64_e32 v[94:95], v[0:1]
	v_mov_b64_e32 v[96:97], v[0:1]
	v_mov_b64_e32 v[98:99], v[0:1]
	v_mov_b64_e32 v[100:101], v[0:1]
	v_mov_b64_e32 v[102:103], v[0:1]
	v_mov_b64_e32 v[104:105], v[0:1]
	v_mov_b64_e32 v[106:107], v[0:1]
	v_mov_b64_e32 v[108:109], v[0:1]
	v_mov_b64_e32 v[110:111], v[0:1]
	v_mov_b64_e32 v[112:113], v[0:1]
	v_mov_b64_e32 v[114:115], v[0:1]
	v_mov_b64_e32 v[116:117], v[0:1]
	v_mov_b64_e32 v[118:119], v[0:1]
	v_mov_b64_e32 v[120:121], v[0:1]
	v_mov_b64_e32 v[122:123], v[0:1]
	v_mov_b64_e32 v[124:125], v[0:1]
	v_mov_b64_e32 v[126:127], v[0:1]

.LBB0_1728:
	s_ashr_i32 s19, s18, 31
	s_lshl_b64 s[22:23], s[18:19], 19
	s_add_u32 s22, s37, s22
	s_addc_u32 s23, s38, s23
	s_and_b64 s[24:25], s[4:5], exec
	s_cselect_b32 s1, s23, s27
	s_cselect_b32 s19, s22, s26
	s_ashr_i32 s21, s20, 31
	s_lshl_b64 s[24:25], s[20:21], 19
	s_add_u32 s24, s39, s24
	s_addc_u32 s25, s40, s25
	s_and_b64 s[28:29], s[4:5], exec
	s_cselect_b32 s21, s25, s7
	s_cselect_b32 s30, s24, s6
	s_add_u32 s31, s6, 0x10000
	s_addc_u32 s34, s7, 0
	s_add_u32 s6, s26, 0x40080
	v_mov_b32_e32 v0, 0
	s_addc_u32 s7, s27, 0
	s_mov_b32 s35, -2
	v_mov_b32_e32 v1, v0
	v_mov_b64_e32 v[2:3], v[0:1]
	v_mov_b64_e32 v[4:5], v[0:1]
	v_mov_b64_e32 v[6:7], v[0:1]
	v_mov_b64_e32 v[8:9], v[0:1]
	v_mov_b64_e32 v[10:11], v[0:1]
	v_mov_b64_e32 v[12:13], v[0:1]
	v_mov_b64_e32 v[14:15], v[0:1]
	v_mov_b64_e32 v[16:17], v[0:1]
	v_mov_b64_e32 v[18:19], v[0:1]
	v_mov_b64_e32 v[20:21], v[0:1]
	v_mov_b64_e32 v[22:23], v[0:1]
	v_mov_b64_e32 v[24:25], v[0:1]
	v_mov_b64_e32 v[26:27], v[0:1]
	v_mov_b64_e32 v[28:29], v[0:1]
	v_mov_b64_e32 v[30:31], v[0:1]
	v_mov_b64_e32 v[32:33], v[0:1]
	v_mov_b64_e32 v[34:35], v[0:1]
	v_mov_b64_e32 v[36:37], v[0:1]
	v_mov_b64_e32 v[38:39], v[0:1]
	v_mov_b64_e32 v[40:41], v[0:1]
	v_mov_b64_e32 v[42:43], v[0:1]
	v_mov_b64_e32 v[44:45], v[0:1]
	v_mov_b64_e32 v[46:47], v[0:1]
	v_mov_b64_e32 v[48:49], v[0:1]
	v_mov_b64_e32 v[50:51], v[0:1]
	v_mov_b64_e32 v[52:53], v[0:1]
	v_mov_b64_e32 v[54:55], v[0:1]
	v_mov_b64_e32 v[56:57], v[0:1]
	v_mov_b64_e32 v[58:59], v[0:1]
	v_mov_b64_e32 v[60:61], v[0:1]
	v_mov_b64_e32 v[62:63], v[0:1]
	v_mov_b64_e32 v[64:65], v[0:1]
	v_mov_b64_e32 v[66:67], v[0:1]
	v_mov_b64_e32 v[68:69], v[0:1]
	v_mov_b64_e32 v[70:71], v[0:1]
	v_mov_b64_e32 v[72:73], v[0:1]
	v_mov_b64_e32 v[74:75], v[0:1]
	v_mov_b64_e32 v[76:77], v[0:1]
	v_mov_b64_e32 v[78:79], v[0:1]
	v_mov_b64_e32 v[80:81], v[0:1]
	v_mov_b64_e32 v[82:83], v[0:1]
	v_mov_b64_e32 v[84:85], v[0:1]
	v_mov_b64_e32 v[86:87], v[0:1]
	v_mov_b64_e32 v[88:89], v[0:1]
	v_mov_b64_e32 v[90:91], v[0:1]
	v_mov_b64_e32 v[92:93], v[0:1]
	v_mov_b64_e32 v[94:95], v[0:1]
	v_mov_b64_e32 v[96:97], v[0:1]
	v_mov_b64_e32 v[98:99], v[0:1]
	v_mov_b64_e32 v[100:101], v[0:1]
	v_mov_b64_e32 v[102:103], v[0:1]
	v_mov_b64_e32 v[104:105], v[0:1]
	v_mov_b64_e32 v[106:107], v[0:1]
	v_mov_b64_e32 v[108:109], v[0:1]
	v_mov_b64_e32 v[110:111], v[0:1]
	v_mov_b64_e32 v[112:113], v[0:1]
	v_mov_b64_e32 v[114:115], v[0:1]
	v_mov_b64_e32 v[116:117], v[0:1]
	v_mov_b64_e32 v[118:119], v[0:1]
	v_mov_b64_e32 v[120:121], v[0:1]
	v_mov_b64_e32 v[122:123], v[0:1]
	v_mov_b64_e32 v[124:125], v[0:1]
	v_mov_b64_e32 v[126:127], v[0:1]

.LBB0_2518:
	s_add_u32 s62, s30, 0x10000
	s_addc_u32 s63, s31, 0
	s_add_u32 s30, s34, 0xc000
	v_mov_b32_e32 v0, 0
	s_addc_u32 s31, s35, 0
	s_mov_b32 s64, -2
	v_mov_b32_e32 v1, v0
	v_mov_b64_e32 v[2:3], v[0:1]
	v_mov_b64_e32 v[4:5], v[0:1]
	v_mov_b64_e32 v[6:7], v[0:1]
	v_mov_b64_e32 v[8:9], v[0:1]
	v_mov_b64_e32 v[10:11], v[0:1]
	v_mov_b64_e32 v[12:13], v[0:1]
	v_mov_b64_e32 v[14:15], v[0:1]
	v_mov_b64_e32 v[16:17], v[0:1]
	v_mov_b64_e32 v[18:19], v[0:1]
	v_mov_b64_e32 v[20:21], v[0:1]
	v_mov_b64_e32 v[22:23], v[0:1]
	v_mov_b64_e32 v[24:25], v[0:1]
	v_mov_b64_e32 v[26:27], v[0:1]
	v_mov_b64_e32 v[28:29], v[0:1]
	v_mov_b64_e32 v[30:31], v[0:1]
	v_mov_b64_e32 v[32:33], v[0:1]
	v_mov_b64_e32 v[34:35], v[0:1]
	v_mov_b64_e32 v[36:37], v[0:1]
	v_mov_b64_e32 v[38:39], v[0:1]
	v_mov_b64_e32 v[40:41], v[0:1]
	v_mov_b64_e32 v[42:43], v[0:1]
	v_mov_b64_e32 v[44:45], v[0:1]
	v_mov_b64_e32 v[46:47], v[0:1]
	v_mov_b64_e32 v[48:49], v[0:1]
	v_mov_b64_e32 v[50:51], v[0:1]
	v_mov_b64_e32 v[52:53], v[0:1]
	v_mov_b64_e32 v[54:55], v[0:1]
	v_mov_b64_e32 v[56:57], v[0:1]
	v_mov_b64_e32 v[58:59], v[0:1]
	v_mov_b64_e32 v[60:61], v[0:1]
	v_mov_b64_e32 v[62:63], v[0:1]
	v_mov_b64_e32 v[64:65], v[0:1]
	v_mov_b64_e32 v[66:67], v[0:1]
	v_mov_b64_e32 v[68:69], v[0:1]
	v_mov_b64_e32 v[70:71], v[0:1]
	v_mov_b64_e32 v[72:73], v[0:1]
	v_mov_b64_e32 v[74:75], v[0:1]
	v_mov_b64_e32 v[76:77], v[0:1]
	v_mov_b64_e32 v[78:79], v[0:1]
	v_mov_b64_e32 v[80:81], v[0:1]
	v_mov_b64_e32 v[82:83], v[0:1]
	v_mov_b64_e32 v[84:85], v[0:1]
	v_mov_b64_e32 v[86:87], v[0:1]
	v_mov_b64_e32 v[88:89], v[0:1]
	v_mov_b64_e32 v[90:91], v[0:1]
	v_mov_b64_e32 v[92:93], v[0:1]
	v_mov_b64_e32 v[94:95], v[0:1]
	v_mov_b64_e32 v[96:97], v[0:1]
	v_mov_b64_e32 v[98:99], v[0:1]
	v_mov_b64_e32 v[100:101], v[0:1]
	v_mov_b64_e32 v[102:103], v[0:1]
	v_mov_b64_e32 v[104:105], v[0:1]
	v_mov_b64_e32 v[106:107], v[0:1]
	v_mov_b64_e32 v[108:109], v[0:1]
	v_mov_b64_e32 v[110:111], v[0:1]
	v_mov_b64_e32 v[112:113], v[0:1]
	v_mov_b64_e32 v[114:115], v[0:1]
	v_mov_b64_e32 v[116:117], v[0:1]
	v_mov_b64_e32 v[118:119], v[0:1]
	v_mov_b64_e32 v[120:121], v[0:1]
	v_mov_b64_e32 v[122:123], v[0:1]
	v_mov_b64_e32 v[124:125], v[0:1]
	v_mov_b64_e32 v[126:127], v[0:1]
